# LRU chunk start: previous-chunk output-tile stores moved after the prefetch-load vmcnt waits so the waits no longer cover the just-issued stores
# baseline (speedup 1.0000x reference)
; #define LAS __attribute__((address_space(3)))
; __device__ __forceinline__ float bf_lo(unsigned w) { return __uint_as_float(w << 16); }
; __device__ __forceinline__ float bf_hi(unsigned w) { return __uint_as_float(w & 0xffff0000u); }
; __device__ __forceinline__ unsigned cvt_pk_bf16(float lo, float hi) { unsigned r; asm volatile("v_cvt_pk_bf16_f32 %0, %1, %2" : "=v"(r) : "v"(lo), "v"(hi)); return r; }
; __device__ __forceinline__ void lru_chain(unsigned char* ws_, const float* const* in_, int l_, LAS unsigned char* lds, int tid, int bid, int G) {
;     ...
;             if (chunk > 0) {
; #pragma unroll
;                 for (int i = 0; i < 2; ++i) { const int idx = tid + 512 * i; const int row = idx >> 3, ch = idx & 7;
;                     *(u32x4*)(X.MIX + ((size_t)b * SEQ + t0 - 128 + row) * DM + AW + CW + c0 + ch * 8) = *(const LAS u32x4*)(OT + row * 144 + ch * 16); }
;             }
; #pragma unroll
;             for (int i = 0; i < 2; ++i) { const int idx = tid + 512 * i; const int row = idx >> 3, ch = idx & 7; *(LAS u32x4*)(GT + row * 144 + ch * 16) = P.g[i]; }
;             { f32x4 xv[5][2];
; #pragma unroll
;               for (int rr = 0; rr < 5; ++rr) { const u32x4 v = P.x[rr]; xv[rr][0] = (f32x4){bf_lo(v.x), bf_hi(v.x), bf_lo(v.y), bf_hi(v.y)}; xv[rr][1] = (f32x4){bf_lo(v.z), bf_hi(v.z), bf_lo(v.w), bf_hi(v.w)}; }
; #pragma unroll
;               for (int tk = 0; tk < 2; ++tk) { f32x4 u0 = cbv[0], u1 = cbv[1];
; #pragma unroll
;                   for (int k = 0; k < 4; ++k) { u0 += cwv[k][0] * xv[tk + k][0]; u1 += cwv[k][1] * xv[tk + k][1]; }
;                   const int tok = 2 * tp + tk;
;                   u32x4 pw; pw.x = cvt_pk_bf16(u0[0], u0[1]); pw.y = cvt_pk_bf16(u0[2], u0[3]); pw.z = cvt_pk_bf16(u1[0], u1[1]); pw.w = cvt_pk_bf16(u1[2], u1[3]);
;                   *(LAS u32x4*)(UB + tok * 144 + cg8 * 16) = pw;
;                   *(LAS f32x4*)(B_ + tok * 68 + cg8 * 8) = u0; *(LAS f32x4*)(B_ + tok * 68 + cg8 * 8 + 4) = u1; } }
;             __syncthreads();
;             if (chunk < 15) lru_load(X, b, h, chunk + 1, tid, P);
.LBB0_187:
.LBB0_189:
	s_waitcnt vmcnt(2)
	v_lshlrev_b32_e32 v2, 16, v4
	v_and_b32_e32 v3, 0xffff0000, v4
	v_lshlrev_b32_e32 v72, 16, v5
	v_and_b32_e32 v73, 0xffff0000, v5
	v_lshlrev_b32_e32 v74, 16, v6
	v_and_b32_e32 v75, 0xffff0000, v6
	v_lshlrev_b32_e32 v76, 16, v7
	v_and_b32_e32 v77, 0xffff0000, v7
	v_lshlrev_b32_e32 v84, 16, v8
	v_and_b32_e32 v85, 0xffff0000, v8
	v_lshlrev_b32_e32 v86, 16, v9
	v_and_b32_e32 v87, 0xffff0000, v9
	v_lshlrev_b32_e32 v88, 16, v10
	v_and_b32_e32 v89, 0xffff0000, v10
	v_lshlrev_b32_e32 v90, 16, v11
	v_and_b32_e32 v91, 0xffff0000, v11
	v_pk_fma_f32 v[2:3], v[28:29], v[2:3], v[20:21]
	v_pk_fma_f32 v[72:73], v[30:31], v[72:73], v[22:23]
	v_pk_fma_f32 v[74:75], v[24:25], v[74:75], v[16:17]
	v_pk_fma_f32 v[76:77], v[26:27], v[76:77], v[18:19]
	v_add_u32_e32 v1, v157, v164
	v_lshlrev_b32_e32 v92, 16, v12
	v_and_b32_e32 v93, 0xffff0000, v12
	v_lshlrev_b32_e32 v94, 16, v13
	v_and_b32_e32 v95, 0xffff0000, v13
	v_lshlrev_b32_e32 v96, 16, v14
	v_and_b32_e32 v97, 0xffff0000, v14
	v_lshlrev_b32_e32 v98, 16, v15
	v_and_b32_e32 v99, 0xffff0000, v15
	v_pk_fma_f32 v[72:73], v[38:39], v[86:87], v[72:73]
	v_pk_fma_f32 v[2:3], v[36:37], v[84:85], v[2:3]
	v_pk_fma_f32 v[76:77], v[34:35], v[90:91], v[76:77]
	v_pk_fma_f32 v[74:75], v[32:33], v[88:89], v[74:75]
	s_waitcnt vmcnt(1)
	ds_write_b128 v1, v[64:67]
	v_add_u32_e32 v1, v157, v165
	v_lshlrev_b32_e32 v100, 16, v56
	v_and_b32_e32 v101, 0xffff0000, v56
	v_lshlrev_b32_e32 v102, 16, v57
	v_and_b32_e32 v103, 0xffff0000, v57
	v_lshlrev_b32_e32 v188, 16, v58
	v_and_b32_e32 v189, 0xffff0000, v58
	v_lshlrev_b32_e32 v206, 16, v59
	v_and_b32_e32 v207, 0xffff0000, v59
	v_pk_fma_f32 v[2:3], v[44:45], v[92:93], v[2:3]
	v_pk_fma_f32 v[72:73], v[46:47], v[94:95], v[72:73]
	v_pk_fma_f32 v[80:81], v[40:41], v[96:97], v[74:75]
	v_pk_fma_f32 v[76:77], v[42:43], v[98:99], v[76:77]
	s_waitcnt vmcnt(0)
	ds_write_b128 v1, v[68:71]
	v_pk_fma_f32 v[74:75], v[54:55], v[102:103], v[72:73]
	v_pk_fma_f32 v[72:73], v[52:53], v[100:101], v[2:3]
	v_pk_fma_f32 v[78:79], v[50:51], v[206:207], v[76:77]
	v_pk_fma_f32 v[76:77], v[48:49], v[188:189], v[80:81]
	v_cvt_pk_bf16_f32 v80, v72, v73
	v_cvt_pk_bf16_f32 v81, v74, v75
	v_pk_fma_f32 v[2:3], v[28:29], v[84:85], v[20:21]
	v_cvt_pk_bf16_f32 v82, v76, v77
	v_cvt_pk_bf16_f32 v83, v78, v79
	ds_write_b128 v199, v[80:83]
	ds_write_b128 v200, v[72:75] offset:53248
	ds_write_b128 v200, v[76:79] offset:53264
	v_pk_fma_f32 v[72:73], v[30:31], v[86:87], v[22:23]
	v_pk_fma_f32 v[74:75], v[24:25], v[88:89], v[16:17]
	v_pk_fma_f32 v[76:77], v[26:27], v[90:91], v[18:19]
	v_pk_fma_f32 v[72:73], v[38:39], v[94:95], v[72:73]
	v_pk_fma_f32 v[2:3], v[36:37], v[92:93], v[2:3]
	v_pk_fma_f32 v[76:77], v[34:35], v[98:99], v[76:77]
	v_pk_fma_f32 v[74:75], v[32:33], v[96:97], v[74:75]
	v_lshlrev_b32_e32 v208, 16, v60
	v_and_b32_e32 v209, 0xffff0000, v60
	v_lshlrev_b32_e32 v210, 16, v61
	v_and_b32_e32 v211, 0xffff0000, v61
	v_lshlrev_b32_e32 v212, 16, v62
	v_and_b32_e32 v213, 0xffff0000, v62
	v_lshlrev_b32_e32 v214, 16, v63
	v_and_b32_e32 v215, 0xffff0000, v63
	v_pk_fma_f32 v[2:3], v[44:45], v[100:101], v[2:3]
	v_pk_fma_f32 v[72:73], v[46:47], v[102:103], v[72:73]
	v_pk_fma_f32 v[80:81], v[40:41], v[188:189], v[74:75]
	v_pk_fma_f32 v[76:77], v[42:43], v[206:207], v[76:77]
	v_pk_fma_f32 v[74:75], v[54:55], v[210:211], v[72:73]
	v_pk_fma_f32 v[72:73], v[52:53], v[208:209], v[2:3]
	v_pk_fma_f32 v[78:79], v[50:51], v[214:215], v[76:77]
	v_pk_fma_f32 v[76:77], v[48:49], v[212:213], v[80:81]
	v_cvt_pk_bf16_f32 v80, v72, v73
	v_cvt_pk_bf16_f32 v81, v74, v75
	s_cmp_eq_u32 s85, 15
	v_cvt_pk_bf16_f32 v82, v76, v77
	v_cvt_pk_bf16_f32 v83, v78, v79
	ds_write_b128 v201, v[80:83]
	ds_write_b128 v202, v[72:75] offset:53248
	ds_write_b128 v202, v[76:79] offset:53264
	s_cmp_eq_u32 s85, 0
	s_cbranch_scc1 .Lot_skip_st
	s_lshl_b32 s2, s85, 7
	v_add_u32_e32 v1, v158, v164
	s_add_u32 s2, s83, s2
	ds_read_b128 v[84:87], v1 offset:18432
	v_add_u32_e32 v1, v158, v165
	s_addc_u32 s3, s84, 0
	ds_read_b128 v[88:91], v1 offset:18432
	v_lshl_add_u64 v[2:3], s[2:3], 0, v[116:117]
	v_lshlrev_b64 v[2:3], 11, v[2:3]
	v_lshl_add_u64 v[2:3], v[136:137], 0, v[2:3]
	v_lshl_add_u64 v[92:93], s[2:3], 0, v[120:121]
	v_lshlrev_b64 v[92:93], 11, v[92:93]
	v_lshl_add_u64 v[92:93], v[136:137], 0, v[92:93]
	s_waitcnt lgkmcnt(1)
	global_store_dwordx4 v[2:3], v[84:87], off offset:1280
	s_waitcnt lgkmcnt(0)
	global_store_dwordx4 v[92:93], v[88:91], off offset:1280
.Lot_skip_st:
	s_cmp_eq_u32 s85, 15
	s_waitcnt lgkmcnt(0)
	s_barrier
	s_cbranch_scc1 .LBB0_201
	s_lshl_b32 s2, s85, 7
	v_add_u32_e32 v1, s2, v152
	v_mov_b32_e32 v8, v0
	v_mov_b32_e32 v9, v0
	v_add_u32_e32 v64, 0x7d, v1
	v_mov_b32_e32 v10, v0
	v_mov_b32_e32 v11, v0
	v_mov_b64_e32 v[4:5], v[8:9]
	v_cmp_lt_i32_e32 vcc, -1, v64
	v_mov_b64_e32 v[6:7], v[10:11]
	s_and_saveexec_b64 s[26:27], vcc
	s_cbranch_execz .LBB0_192
	v_mov_b64_e32 v[2:3], s[28:29]
	v_mad_u64_u32 v[2:3], s[4:5], v64, s71, v[2:3]
	v_lshl_add_u64 v[2:3], s[60:61], 1, v[2:3]
	v_mov_b32_e32 v133, v0
	v_lshl_add_u64 v[2:3], v[2:3], 0, v[132:133]
	v_add_co_u32_e32 v2, vcc, 0x1000, v2
	s_nop 1
	v_addc_co_u32_e32 v3, vcc, 0, v3, vcc
	global_load_dwordx4 v[4:7], v[2:3], off
